# norm rows assigned to the XCD whose GEMM tiles produce and consume them (row r -> block on XCD (r/128)%8)
# baseline (speedup 1.0000x reference)
.LBB0_209:
	v_readlane_b32 s3, v248, 11
	s_mul_i32 s1, s3, 0x51000
	v_readlane_b32 s2, v251, 61
	v_mov_b32_e32 v1, v162
	v_mov_b32_e32 v0, v162
	s_mul_hi_u32 s0, s3, 0x51000
	s_add_u32 s16, s2, s1
	v_readlane_b32 s1, v251, 62
	s_addc_u32 s17, s1, s0
	v_ashrrev_i32_e32 v0, 6, v0
	v_readlane_b32 s0, v251, 60
	s_nop 1
	v_readlane_b32 s100, v251, 36
	s_cmpk_lg_u32 s94, 0x200
	s_cbranch_scc1 .Lnrm_orig0
	s_lshr_b32 s101, s100, 3
	s_lshl_b32 s101, s101, 2
	v_add_u32_e32 v0, s101, v0
	s_and_b32 s100, s100, 7
	s_lshl_b32 s100, s100, 7
	v_lshrrev_b32_e32 v255, 7, v0
	v_and_b32_e32 v0, 0x7f, v0
	v_lshl_add_u32 v0, v255, 10, v0
	v_add_u32_e32 v0, s100, v0
	s_branch .Lnrm_done0
.Lnrm_orig0:
	v_add_u32_e32 v0, s0, v0
.Lnrm_done0:
	s_movk_i32 s0, 0x4800
	v_cmp_gt_i32_e32 vcc, s0, v0
	s_mul_hi_u32 s0, s3, 0x3000
	v_writelane_b32 v248, s0, 12
	s_mul_i32 s0, s3, 0x3000
	v_writelane_b32 v248, s0, 13
	s_and_saveexec_b64 s[0:1], vcc
	s_mov_b64 s[6:7], 0x1000
	s_cbranch_execz .LBB0_212
	v_and_b32_e32 v6, 63, v1
	v_and_b32_e32 v1, 64, v196
	v_add_u32_e32 v1, 64, v1
	v_xor_b32_e32 v2, 32, v196
	v_cmp_lt_i32_e32 vcc, v2, v1
	v_readlane_b32 s40, v251, 38
	v_readlane_b32 s48, v251, 46
	v_cndmask_b32_e32 v2, v196, v2, vcc
	v_lshlrev_b32_e32 v10, 2, v2
	v_xor_b32_e32 v2, 16, v196
	v_cmp_lt_i32_e32 vcc, v2, v1
	v_readlane_b32 s49, v251, 47
	v_readlane_b32 s50, v251, 48
	v_cndmask_b32_e32 v2, v196, v2, vcc
	v_lshlrev_b32_e32 v11, 2, v2
	v_xor_b32_e32 v2, 8, v196
	v_cmp_lt_i32_e32 vcc, v2, v1
	v_readlane_b32 s51, v251, 49
	v_readlane_b32 s52, v251, 50
	v_cndmask_b32_e32 v2, v196, v2, vcc
	v_lshlrev_b32_e32 v12, 2, v2
	v_xor_b32_e32 v2, 4, v196
	v_cmp_lt_i32_e32 vcc, v2, v1
	v_readlane_b32 s53, v251, 51
	v_readlane_b32 s54, v251, 52
	v_cndmask_b32_e32 v2, v196, v2, vcc
	v_lshlrev_b32_e32 v13, 2, v2
	v_xor_b32_e32 v2, 2, v196
	v_cmp_lt_i32_e32 vcc, v2, v1
	v_readlane_b32 s55, v251, 53
	s_mov_b64 s[48:49], s[52:53]
	v_cndmask_b32_e32 v2, v196, v2, vcc
	v_lshlrev_b32_e32 v14, 2, v2
	v_xor_b32_e32 v2, 1, v196
	v_cmp_lt_i32_e32 vcc, v2, v1
	v_readlane_b32 s2, v248, 13
	s_add_u32 s2, s48, s2
	v_cndmask_b32_e32 v1, v196, v2, vcc
	v_lshlrev_b32_e32 v15, 2, v1
	v_ashrrev_i32_e32 v1, 31, v0
	v_readlane_b32 s3, v248, 12
	v_lshlrev_b32_e32 v8, 3, v6
	v_lshlrev_b64 v[4:5], 11, v[0:1]
	s_addc_u32 s3, s49, s3
	v_or_b32_e32 v16, 0x200, v8
	v_lshlrev_b32_e32 v96, 5, v6
	v_lshl_or_b32 v4, v6, 4, v4
	v_lshlrev_b64 v[6:7], 12, v[0:1]
	v_lshl_add_u64 v[2:3], s[2:3], 0, v[96:97]
	v_or_b32_e32 v6, v6, v96
	s_mov_b64 s[2:3], 0
	v_lshlrev_b32_e32 v96, 2, v8
	v_lshlrev_b32_e32 v8, 2, v16
	v_readlane_b32 s41, v251, 39
	v_readlane_b32 s42, v251, 40
	v_readlane_b32 s43, v251, 41
	v_readlane_b32 s44, v251, 42
	v_readlane_b32 s45, v251, 43
	v_readlane_b32 s46, v251, 44
	v_readlane_b32 s47, v251, 45
	s_mov_b64 s[50:51], s[54:55]

.LBB0_388:
	s_or_b64 exec, exec, s[0:1]
	s_waitcnt lgkmcnt(0)
	v_mov_b32_e32 v0, v162
	v_mov_b32_e32 v1, v162
	s_barrier
	v_readlane_b32 s0, v251, 60
	v_ashrrev_i32_e32 v1, 6, v1
	s_nop 0
	v_readlane_b32 s100, v251, 36
	s_cmpk_lg_u32 s94, 0x200
	s_cbranch_scc1 .Lnrm_orig1
	s_lshr_b32 s101, s100, 3
	s_lshl_b32 s101, s101, 2
	v_add_u32_e32 v12, s101, v1
	s_and_b32 s100, s100, 7
	s_lshl_b32 s100, s100, 7
	v_lshrrev_b32_e32 v255, 7, v12
	v_and_b32_e32 v12, 0x7f, v12
	v_lshl_add_u32 v12, v255, 10, v12
	v_add_u32_e32 v12, s100, v12
	s_branch .Lnrm_done1
.Lnrm_orig1:
	v_add_u32_e32 v12, s0, v1
.Lnrm_done1:
	s_movk_i32 s0, 0x4800
	v_cmp_gt_i32_e32 vcc, s0, v12
	s_and_saveexec_b64 s[0:1], vcc
	s_mov_b64 s[10:11], 0x1000
	s_cbranch_execz .LBB0_391
	v_and_b32_e32 v1, 63, v0
	v_mbcnt_hi_u32_b32 v0, -1, v195
	v_and_b32_e32 v2, 64, v0
	v_add_u32_e32 v2, 64, v2
	v_xor_b32_e32 v3, 32, v0
	v_cmp_lt_i32_e32 vcc, v3, v2
	v_readlane_b32 s40, v251, 38
	s_add_u32 s2, s16, 0x3000
	v_cndmask_b32_e32 v3, v0, v3, vcc
	v_lshlrev_b32_e32 v29, 2, v3
	v_xor_b32_e32 v3, 16, v0
	v_cmp_lt_i32_e32 vcc, v3, v2
	v_readlane_b32 s48, v251, 46
	v_readlane_b32 s49, v251, 47
	v_cndmask_b32_e32 v3, v0, v3, vcc
	v_lshlrev_b32_e32 v32, 2, v3
	v_xor_b32_e32 v3, 8, v0
	v_cmp_lt_i32_e32 vcc, v3, v2
	v_readlane_b32 s50, v251, 48
	v_readlane_b32 s51, v251, 49
	v_cndmask_b32_e32 v3, v0, v3, vcc
	v_lshlrev_b32_e32 v33, 2, v3
	v_xor_b32_e32 v3, 4, v0
	v_cmp_lt_i32_e32 vcc, v3, v2
	v_readlane_b32 s52, v251, 50
	v_readlane_b32 s53, v251, 51
	v_cndmask_b32_e32 v3, v0, v3, vcc
	v_lshlrev_b32_e32 v34, 2, v3
	v_xor_b32_e32 v3, 2, v0
	v_cmp_lt_i32_e32 vcc, v3, v2
	s_addc_u32 s3, s17, 0
	v_readlane_b32 s54, v251, 52
	v_cndmask_b32_e32 v3, v0, v3, vcc
	v_lshlrev_b32_e32 v35, 2, v3
	v_xor_b32_e32 v3, 1, v0
	v_readlane_b32 s55, v251, 53
	s_mov_b64 s[48:49], s[52:53]
	v_readlane_b32 s4, v248, 13
	v_cmp_lt_i32_e32 vcc, v3, v2
	s_add_u32 s4, s48, s4
	v_readlane_b32 s6, v248, 12
	v_cndmask_b32_e32 v0, v0, v3, vcc
	s_addc_u32 s7, s49, s6
	v_lshlrev_b32_e32 v36, 2, v0
	v_lshlrev_b32_e32 v0, 3, v1
	s_add_u32 s6, s4, 0x1000
	v_or_b32_e32 v2, 0x200, v0
	s_addc_u32 s7, s7, 0
	v_lshlrev_b32_e32 v96, 2, v2
	v_ashrrev_i32_e32 v13, 31, v12
	v_lshl_add_u64 v[14:15], s[6:7], 0, v[96:97]
	v_lshlrev_b32_e32 v96, 5, v1
	v_lshlrev_b64 v[18:19], 11, v[12:13]
	v_lshlrev_b64 v[20:21], 12, v[12:13]
	v_lshl_add_u64 v[16:17], s[6:7], 0, v[96:97]
	v_lshl_or_b32 v18, v1, 4, v18
	v_or_b32_e32 v20, v20, v96
	s_mov_b64 s[6:7], 0
	v_lshlrev_b32_e32 v96, 2, v0
	v_lshlrev_b32_e32 v22, 2, v2
	v_readlane_b32 s41, v251, 39
	v_readlane_b32 s42, v251, 40
	v_readlane_b32 s43, v251, 41
	v_readlane_b32 s44, v251, 42
	v_readlane_b32 s45, v251, 43
	v_readlane_b32 s46, v251, 44
	v_readlane_b32 s47, v251, 45
	s_mov_b64 s[50:51], s[54:55]

.LBB0_1294:
	s_or_b64 exec, exec, s[2:3]
	s_waitcnt lgkmcnt(0)
	v_mov_b32_e32 v0, v162
	v_mov_b32_e32 v1, v162
	s_barrier
	v_readlane_b32 s2, v251, 60
	v_ashrrev_i32_e32 v1, 6, v1
	s_lshl_b32 s38, s10, 7
	v_readlane_b32 s100, v251, 36
	s_cmpk_lg_u32 s94, 0x200
	s_cbranch_scc1 .Lnrm_orig2
	s_lshr_b32 s101, s100, 3
	s_lshl_b32 s101, s101, 2
	v_add_u32_e32 v12, s101, v1
	s_and_b32 s100, s100, 7
	s_lshl_b32 s100, s100, 7
	v_lshrrev_b32_e32 v255, 7, v12
	v_and_b32_e32 v12, 0x7f, v12
	v_lshl_add_u32 v12, v255, 10, v12
	v_add_u32_e32 v12, s100, v12
	s_branch .Lnrm_done2
.Lnrm_orig2:
	v_add_u32_e32 v12, s2, v1
.Lnrm_done2:
	v_cmp_gt_i32_e32 vcc, s38, v12
	s_and_saveexec_b64 s[2:3], vcc
	v_readlane_b32 s8, v249, 60
	s_mov_b64 s[16:17], 0x1000
	v_readlane_b32 s9, v249, 61
	s_cbranch_execz .LBB0_1297
	v_and_b32_e32 v1, 63, v0
	v_and_b32_e32 v0, 64, v196
	v_add_u32_e32 v0, 64, v0
	v_xor_b32_e32 v2, 32, v196
	v_cmp_lt_i32_e32 vcc, v2, v0
	s_mov_b64 s[6:7], s[82:83]
	s_add_u32 s6, s6, 0x6000
	v_cndmask_b32_e32 v2, v196, v2, vcc
	v_lshlrev_b32_e32 v29, 2, v2
	v_xor_b32_e32 v2, 16, v196
	v_cmp_lt_i32_e32 vcc, v2, v0
	v_readlane_b32 s40, v251, 38
	s_addc_u32 s7, s7, 0
	v_cndmask_b32_e32 v2, v196, v2, vcc
	v_lshlrev_b32_e32 v32, 2, v2
	v_xor_b32_e32 v2, 8, v196
	v_cmp_lt_i32_e32 vcc, v2, v0
	v_readlane_b32 s52, v251, 50
	v_readlane_b32 s9, v248, 13
	v_cndmask_b32_e32 v2, v196, v2, vcc
	v_lshlrev_b32_e32 v33, 2, v2
	v_xor_b32_e32 v2, 4, v196
	v_cmp_lt_i32_e32 vcc, v2, v0
	v_readlane_b32 s53, v251, 51
	s_add_u32 s12, s52, s9
	v_cndmask_b32_e32 v2, v196, v2, vcc
	v_lshlrev_b32_e32 v34, 2, v2
	v_xor_b32_e32 v2, 2, v196
	v_cmp_lt_i32_e32 vcc, v2, v0
	v_readlane_b32 s9, v248, 12
	s_addc_u32 s13, s53, s9
	v_cndmask_b32_e32 v2, v196, v2, vcc
	v_lshlrev_b32_e32 v35, 2, v2
	v_xor_b32_e32 v2, 1, v196
	v_cmp_lt_i32_e32 vcc, v2, v0
	s_add_u32 s12, s12, 0x2000
	s_addc_u32 s13, s13, 0
	v_cndmask_b32_e32 v0, v196, v2, vcc
	v_lshlrev_b32_e32 v36, 2, v0
	v_lshlrev_b32_e32 v0, 3, v1
	v_or_b32_e32 v2, 0x200, v0
	v_lshlrev_b32_e32 v96, 2, v2
	v_ashrrev_i32_e32 v13, 31, v12
	v_lshl_add_u64 v[14:15], s[12:13], 0, v[96:97]
	v_lshlrev_b32_e32 v96, 5, v1
	v_lshlrev_b64 v[18:19], 11, v[12:13]
	v_lshlrev_b64 v[20:21], 12, v[12:13]
	v_lshl_add_u64 v[16:17], s[12:13], 0, v[96:97]
	v_lshl_or_b32 v18, v1, 4, v18
	v_or_b32_e32 v20, v20, v96
	s_mov_b64 s[12:13], 0
	v_lshlrev_b32_e32 v96, 2, v0
	v_lshlrev_b32_e32 v22, 2, v2
	v_readlane_b32 s41, v251, 39
	v_readlane_b32 s42, v251, 40
	v_readlane_b32 s43, v251, 41
	v_readlane_b32 s44, v251, 42
	v_readlane_b32 s45, v251, 43
	v_readlane_b32 s46, v251, 44
	v_readlane_b32 s47, v251, 45
	v_readlane_b32 s48, v251, 46
	v_readlane_b32 s49, v251, 47
	v_readlane_b32 s50, v251, 48
	v_readlane_b32 s51, v251, 49
	v_readlane_b32 s54, v251, 52
	v_readlane_b32 s55, v251, 53
